# up epilogue H stores alternate sc1 nt / nt (policy mix test on top of v70)
# baseline (speedup 1.0000x reference)
; __device__ __forceinline__ unsigned cvt_pk_bf16(float lo, float hi) { unsigned r; asm volatile("v_cvt_pk_bf16_f32 %0, %1, %2" : "=v"(r) : "v"(lo), "v"(hi)); return r; }
;     __device__ __forceinline__ void operator()(const f32x4 (&acc)[2][2][4][2], const Unit& u, int ui, int wr, int wc, int fr, int fq) const {
;     ...
;         const int row0 = u.pm * BM + wr * 64 + fr, col0 = u.pn * HALF + wc * 32 + 8 * fq;
;         float rs[2][4];
; #pragma unroll
;         for (int ai = 0; ai < 2; ++ai)
; #pragma unroll
;             for (int m = 0; m < 4; ++m) rs[ai][m] = row_rstd(lds, ui, ai * HALF + wr * 64 + m * 16 + fr);
; #pragma unroll
;         for (int ai = 0; ai < 2; ++ai)
; #pragma unroll
;             for (int m = 0; m < 4; ++m) { const float r = rs[ai][m]; const int row = row0 + ai * HALF + m * 16;
;                 const float c1 = r * -1.44269504089f, r2 = r * r; u32x4 w;
; #pragma unroll
;                 for (int n = 0; n < 2; ++n)
; #pragma unroll
;                     for (int p = 0; p < 2; ++p) { const f32x2 g = (f32x2){acc[ai][0][m][n][2 * p], acc[ai][0][m][n][2 * p + 1]}, uu = (f32x2){acc[ai][1][m][n][2 * p], acc[ai][1][m][n][2 * p + 1]};
;                         const f32x2 t = g * c1; f32x2 d; d.x = __builtin_amdgcn_exp2f(t.x); d.y = __builtin_amdgcn_exp2f(t.y); d = d + 1.0f;
;                         f32x2 q; q.x = __builtin_amdgcn_rcpf(d.x); q.y = __builtin_amdgcn_rcpf(d.y);
;                         const f32x2 hh = (g * uu) * (q * r2); w[2 * n + p] = cvt_pk_bf16(hh.x, hh.y); }
;                 __builtin_nontemporal_store(w, (u32x4*)(H + (size_t)row * ldh + col0)); }
.LBB0_449:
	v_mov_b32_e32 v140, v147
	v_mov_b32_e32 v167, v164
	v_pk_mul_f32 v[120:121], v[124:125], v[120:121]
	v_add_u32_e32 v171, s35, v140
	v_lshlrev_b32_e32 v140, 2, v171
	v_lshl_add_u32 v140, s48, 10, v140
	v_add_u32_e32 v140, 0x20400, v140
	ds_read2_b32 v[168:169], v140 offset1:16
	ds_read2_b32 v[162:163], v140 offset0:32 offset1:48
	ds_read2_b32 v[142:143], v140 offset0:128 offset1:144
	ds_read2_b32 v[140:141], v140 offset0:160 offset1:176
	v_pk_mul_f32 v[122:123], v[126:127], v[122:123]
	s_waitcnt lgkmcnt(0)
	v_mul_f32_e32 v172, 0xbfb8aa3b, v168
	v_pk_mul_f32 v[174:175], v[124:125], v[172:173] op_sel_hi:[1,0]
	v_pk_mul_f32 v[124:125], v[126:127], v[172:173] op_sel_hi:[1,0]
	v_exp_f32_e32 v174, v174
	v_exp_f32_e32 v175, v175
	v_exp_f32_e32 v124, v124
	v_exp_f32_e32 v125, v125
	v_mul_f32_e32 v168, v168, v168
	v_pk_add_f32 v[174:175], v[174:175], 1.0 op_sel_hi:[1,0]
	v_pk_mul_f32 v[112:113], v[116:117], v[112:113]
	v_rcp_f32_e32 v174, v174
	v_rcp_f32_e32 v175, v175
	v_pk_add_f32 v[124:125], v[124:125], 1.0 op_sel_hi:[1,0]
	v_pk_mul_f32 v[114:115], v[118:119], v[114:115]
	v_rcp_f32_e32 v124, v124
	v_rcp_f32_e32 v125, v125
	v_pk_mul_f32 v[126:127], v[168:169], v[174:175] op_sel_hi:[0,1]
	v_pk_mul_f32 v[120:121], v[120:121], v[126:127]
	v_pk_mul_f32 v[126:127], v[116:117], v[172:173] op_sel_hi:[1,0]
	v_pk_mul_f32 v[124:125], v[168:169], v[124:125] op_sel_hi:[0,1]
	v_exp_f32_e32 v126, v126
	v_exp_f32_e32 v127, v127
	v_pk_mul_f32 v[122:123], v[122:123], v[124:125]
	v_pk_mul_f32 v[124:125], v[118:119], v[172:173] op_sel_hi:[1,0]
	v_cvt_pk_bf16_f32 v120, v120, v121
	v_cvt_pk_bf16_f32 v121, v122, v123
	v_pk_add_f32 v[122:123], v[126:127], 1.0 op_sel_hi:[1,0]
	v_exp_f32_e32 v124, v124
	v_exp_f32_e32 v125, v125
	v_rcp_f32_e32 v122, v122
	v_rcp_f32_e32 v123, v123
	s_lshl_b32 s5, s47, 7
	v_pk_add_f32 v[116:117], v[124:125], 1.0 op_sel_hi:[1,0]
	s_or_b32 s5, s5, s36
	v_rcp_f32_e32 v116, v116
	v_rcp_f32_e32 v117, v117
	v_pk_mul_f32 v[118:119], v[168:169], v[122:123] op_sel_hi:[0,1]
	v_pk_mul_f32 v[112:113], v[112:113], v[118:119]
	v_mul_f32_e32 v118, 0xbfb8aa3b, v169
	v_cvt_pk_bf16_f32 v122, v112, v113
	v_pk_mul_f32 v[112:113], v[168:169], v[116:117] op_sel_hi:[0,1]
	v_pk_mul_f32 v[124:125], v[108:109], v[118:119] op_sel_hi:[1,0]
	v_lshl_add_u32 v170, v167, 3, s5
	v_pk_mul_f32 v[112:113], v[114:115], v[112:113]
	v_exp_f32_e32 v124, v124
	v_exp_f32_e32 v125, v125
	v_lshl_add_u32 v167, s46, 8, v171
	v_ashrrev_i32_e32 v171, 31, v170
	v_cvt_pk_bf16_f32 v123, v112, v113
	v_mov_b64_e32 v[112:113], s[20:21]
	v_pk_mul_f32 v[104:105], v[108:109], v[104:105]
	v_pk_mul_f32 v[108:109], v[110:111], v[118:119] op_sel_hi:[1,0]
	v_mad_i64_i32 v[116:117], s[14:15], v167, s59, v[112:113]
	v_lshlrev_b64 v[114:115], 1, v[170:171]
	v_exp_f32_e32 v108, v108
	v_exp_f32_e32 v109, v109
	v_lshl_add_u64 v[116:117], v[116:117], 0, v[114:115]
	global_store_dwordx4 v[116:117], v[120:123], off sc1 nt
	v_mul_f32_e32 v116, v169, v169
	v_pk_add_f32 v[108:109], v[108:109], 1.0 op_sel_hi:[1,0]
	v_pk_add_f32 v[120:121], v[124:125], 1.0 op_sel_hi:[1,0]
	v_rcp_f32_e32 v108, v108
	v_rcp_f32_e32 v120, v120
	v_rcp_f32_e32 v121, v121
	v_rcp_f32_e32 v109, v109
	v_pk_mul_f32 v[106:107], v[110:111], v[106:107]
	v_pk_mul_f32 v[96:97], v[100:101], v[96:97]
	v_pk_mul_f32 v[110:111], v[116:117], v[120:121] op_sel_hi:[0,1]
	v_pk_mul_f32 v[104:105], v[104:105], v[110:111]
	v_pk_mul_f32 v[110:111], v[100:101], v[118:119] op_sel_hi:[1,0]
	v_pk_mul_f32 v[108:109], v[116:117], v[108:109] op_sel_hi:[0,1]
	v_exp_f32_e32 v110, v110
	v_exp_f32_e32 v111, v111
	v_pk_mul_f32 v[106:107], v[106:107], v[108:109]
	v_pk_mul_f32 v[108:109], v[102:103], v[118:119] op_sel_hi:[1,0]
	v_cvt_pk_bf16_f32 v104, v104, v105
	v_cvt_pk_bf16_f32 v105, v106, v107
	v_pk_add_f32 v[106:107], v[110:111], 1.0 op_sel_hi:[1,0]
	v_exp_f32_e32 v108, v108
	v_exp_f32_e32 v109, v109
	v_rcp_f32_e32 v106, v106
	v_rcp_f32_e32 v107, v107
	v_pk_mul_f32 v[98:99], v[102:103], v[98:99]
	v_pk_add_f32 v[100:101], v[108:109], 1.0 op_sel_hi:[1,0]
	v_pk_mul_f32 v[88:89], v[92:93], v[88:89]
	v_rcp_f32_e32 v100, v100
	v_rcp_f32_e32 v101, v101
	v_pk_mul_f32 v[102:103], v[116:117], v[106:107] op_sel_hi:[0,1]
	v_pk_mul_f32 v[96:97], v[96:97], v[102:103]
	v_pk_mul_f32 v[90:91], v[94:95], v[90:91]
	v_cvt_pk_bf16_f32 v106, v96, v97
	v_pk_mul_f32 v[96:97], v[116:117], v[100:101] op_sel_hi:[0,1]
	v_pk_mul_f32 v[96:97], v[98:99], v[96:97]
	v_mul_f32_e32 v98, 0xbfb8aa3b, v162
	v_pk_mul_f32 v[100:101], v[92:93], v[98:99] op_sel_hi:[1,0]
	v_pk_mul_f32 v[92:93], v[94:95], v[98:99] op_sel_hi:[1,0]
	v_exp_f32_e32 v100, v100
	v_exp_f32_e32 v101, v101
	v_exp_f32_e32 v92, v92
	v_exp_f32_e32 v93, v93
	v_cvt_pk_bf16_f32 v107, v96, v97
	v_pk_add_f32 v[100:101], v[100:101], 1.0 op_sel_hi:[1,0]
	v_add_u32_e32 v96, 16, v167
	v_rcp_f32_e32 v100, v100
	v_rcp_f32_e32 v101, v101
	v_mad_i64_i32 v[96:97], s[14:15], v96, s59, v[112:113]
	v_pk_add_f32 v[92:93], v[92:93], 1.0 op_sel_hi:[1,0]
	v_lshl_add_u64 v[96:97], v[96:97], 0, v[114:115]
	v_rcp_f32_e32 v92, v92
	v_rcp_f32_e32 v93, v93
	global_store_dwordx4 v[96:97], v[104:107], off nt
	v_mul_f32_e32 v96, v162, v162
	v_pk_mul_f32 v[94:95], v[96:97], v[100:101] op_sel_hi:[0,1]
	v_pk_mul_f32 v[88:89], v[88:89], v[94:95]
	v_pk_mul_f32 v[94:95], v[84:85], v[98:99] op_sel_hi:[1,0]
	v_pk_mul_f32 v[92:93], v[96:97], v[92:93] op_sel_hi:[0,1]
	v_exp_f32_e32 v94, v94
	v_exp_f32_e32 v95, v95
	v_pk_mul_f32 v[90:91], v[90:91], v[92:93]
	v_pk_mul_f32 v[92:93], v[86:87], v[98:99] op_sel_hi:[1,0]
	v_cvt_pk_bf16_f32 v88, v88, v89
	v_cvt_pk_bf16_f32 v89, v90, v91
	v_pk_add_f32 v[90:91], v[94:95], 1.0 op_sel_hi:[1,0]
	v_exp_f32_e32 v92, v92
; __device__ __forceinline__ unsigned cvt_pk_bf16(float lo, float hi) { unsigned r; asm volatile("v_cvt_pk_bf16_f32 %0, %1, %2" : "=v"(r) : "v"(lo), "v"(hi)); return r; }
;     __device__ __forceinline__ void operator()(const f32x4 (&acc)[2][2][4][2], const Unit& u, int ui, int wr, int wc, int fr, int fq) const {
;     ...
;         for (int ai = 0; ai < 2; ++ai)
; #pragma unroll
;             for (int m = 0; m < 4; ++m) { const float r = rs[ai][m]; const int row = row0 + ai * HALF + m * 16;
;                 const float c1 = r * -1.44269504089f, r2 = r * r; u32x4 w;
; #pragma unroll
;                 for (int n = 0; n < 2; ++n)
; #pragma unroll
;                     for (int p = 0; p < 2; ++p) { const f32x2 g = (f32x2){acc[ai][0][m][n][2 * p], acc[ai][0][m][n][2 * p + 1]}, uu = (f32x2){acc[ai][1][m][n][2 * p], acc[ai][1][m][n][2 * p + 1]};
;                         const f32x2 t = g * c1; f32x2 d; d.x = __builtin_amdgcn_exp2f(t.x); d.y = __builtin_amdgcn_exp2f(t.y); d = d + 1.0f;
;                         f32x2 q; q.x = __builtin_amdgcn_rcpf(d.x); q.y = __builtin_amdgcn_rcpf(d.y);
;                         const f32x2 hh = (g * uu) * (q * r2); w[2 * n + p] = cvt_pk_bf16(hh.x, hh.y); }
;                 __builtin_nontemporal_store(w, (u32x4*)(H + (size_t)row * ldh + col0)); }
	v_exp_f32_e32 v93, v93
	v_rcp_f32_e32 v90, v90
	v_rcp_f32_e32 v91, v91
	v_pk_mul_f32 v[80:81], v[84:85], v[80:81]
	v_pk_add_f32 v[84:85], v[92:93], 1.0 op_sel_hi:[1,0]
	v_pk_mul_f32 v[82:83], v[86:87], v[82:83]
	v_rcp_f32_e32 v84, v84
	v_rcp_f32_e32 v85, v85
	v_pk_mul_f32 v[86:87], v[96:97], v[90:91] op_sel_hi:[0,1]
	v_pk_mul_f32 v[80:81], v[80:81], v[86:87]
	v_pk_mul_f32 v[72:73], v[76:77], v[72:73]
	v_cvt_pk_bf16_f32 v90, v80, v81
	v_pk_mul_f32 v[80:81], v[96:97], v[84:85] op_sel_hi:[0,1]
	v_pk_mul_f32 v[80:81], v[82:83], v[80:81]
	v_mul_f32_e32 v82, 0xbfb8aa3b, v163
	v_pk_mul_f32 v[84:85], v[76:77], v[82:83] op_sel_hi:[1,0]
	v_pk_mul_f32 v[76:77], v[78:79], v[82:83] op_sel_hi:[1,0]
	v_exp_f32_e32 v84, v84
	v_exp_f32_e32 v85, v85
	v_exp_f32_e32 v76, v76
	v_exp_f32_e32 v77, v77
	v_cvt_pk_bf16_f32 v91, v80, v81
	v_pk_add_f32 v[84:85], v[84:85], 1.0 op_sel_hi:[1,0]
	v_add_u32_e32 v80, 32, v167
	v_rcp_f32_e32 v84, v84
	v_rcp_f32_e32 v85, v85
	v_mad_i64_i32 v[80:81], s[14:15], v80, s59, v[112:113]
	v_pk_add_f32 v[76:77], v[76:77], 1.0 op_sel_hi:[1,0]
	v_lshl_add_u64 v[80:81], v[80:81], 0, v[114:115]
	v_rcp_f32_e32 v76, v76
	v_rcp_f32_e32 v77, v77
	global_store_dwordx4 v[80:81], v[88:91], off sc1 nt
	v_mul_f32_e32 v80, v163, v163
	v_pk_mul_f32 v[74:75], v[78:79], v[74:75]
	v_pk_mul_f32 v[78:79], v[80:81], v[84:85] op_sel_hi:[0,1]
	v_pk_mul_f32 v[72:73], v[72:73], v[78:79]
	v_pk_mul_f32 v[78:79], v[68:69], v[82:83] op_sel_hi:[1,0]
	v_pk_mul_f32 v[76:77], v[80:81], v[76:77] op_sel_hi:[0,1]
	v_exp_f32_e32 v78, v78
	v_exp_f32_e32 v79, v79
	v_pk_mul_f32 v[74:75], v[74:75], v[76:77]
	v_pk_mul_f32 v[76:77], v[70:71], v[82:83] op_sel_hi:[1,0]
	v_cvt_pk_bf16_f32 v72, v72, v73
	v_cvt_pk_bf16_f32 v73, v74, v75
	v_pk_add_f32 v[74:75], v[78:79], 1.0 op_sel_hi:[1,0]
	v_exp_f32_e32 v76, v76
	v_exp_f32_e32 v77, v77
	v_rcp_f32_e32 v74, v74
	v_rcp_f32_e32 v75, v75
	v_pk_mul_f32 v[64:65], v[68:69], v[64:65]
	v_pk_add_f32 v[68:69], v[76:77], 1.0 op_sel_hi:[1,0]
	v_pk_mul_f32 v[66:67], v[70:71], v[66:67]
	v_rcp_f32_e32 v68, v68
	v_rcp_f32_e32 v69, v69
	v_pk_mul_f32 v[70:71], v[80:81], v[74:75] op_sel_hi:[0,1]
	v_pk_mul_f32 v[64:65], v[64:65], v[70:71]
	v_pk_mul_f32 v[56:57], v[60:61], v[56:57]
	v_cvt_pk_bf16_f32 v74, v64, v65
	v_pk_mul_f32 v[64:65], v[80:81], v[68:69] op_sel_hi:[0,1]
	v_pk_mul_f32 v[64:65], v[66:67], v[64:65]
	v_mul_f32_e32 v66, 0xbfb8aa3b, v142
	v_pk_mul_f32 v[68:69], v[60:61], v[66:67] op_sel_hi:[1,0]
	v_pk_mul_f32 v[60:61], v[62:63], v[66:67] op_sel_hi:[1,0]
	v_exp_f32_e32 v68, v68
	v_exp_f32_e32 v69, v69
	v_exp_f32_e32 v60, v60
	v_exp_f32_e32 v61, v61
	v_cvt_pk_bf16_f32 v75, v64, v65
	v_pk_add_f32 v[68:69], v[68:69], 1.0 op_sel_hi:[1,0]
	v_add_u32_e32 v64, 48, v167
	v_rcp_f32_e32 v68, v68
	v_rcp_f32_e32 v69, v69
	v_mad_i64_i32 v[64:65], s[14:15], v64, s59, v[112:113]
	v_pk_add_f32 v[60:61], v[60:61], 1.0 op_sel_hi:[1,0]
	v_lshl_add_u64 v[64:65], v[64:65], 0, v[114:115]
	v_rcp_f32_e32 v60, v60
	v_rcp_f32_e32 v61, v61
	global_store_dwordx4 v[64:65], v[72:75], off nt
	v_add_u32_e32 v65, 0x80, v167
	v_mul_f32_e32 v64, v142, v142
	v_pk_mul_f32 v[58:59], v[62:63], v[58:59]
	v_pk_mul_f32 v[62:63], v[64:65], v[68:69] op_sel_hi:[0,1]
	v_pk_mul_f32 v[56:57], v[56:57], v[62:63]
	v_pk_mul_f32 v[62:63], v[52:53], v[66:67] op_sel_hi:[1,0]
	v_pk_mul_f32 v[60:61], v[64:65], v[60:61] op_sel_hi:[0,1]
	v_exp_f32_e32 v62, v62
	v_exp_f32_e32 v63, v63
	v_pk_mul_f32 v[58:59], v[58:59], v[60:61]
	v_pk_mul_f32 v[60:61], v[54:55], v[66:67] op_sel_hi:[1,0]
	v_cvt_pk_bf16_f32 v56, v56, v57
	v_cvt_pk_bf16_f32 v57, v58, v59
	v_pk_add_f32 v[58:59], v[62:63], 1.0 op_sel_hi:[1,0]
	v_exp_f32_e32 v60, v60
	v_exp_f32_e32 v61, v61
	v_rcp_f32_e32 v58, v58
	v_rcp_f32_e32 v59, v59
	v_pk_mul_f32 v[48:49], v[52:53], v[48:49]
	v_pk_add_f32 v[52:53], v[60:61], 1.0 op_sel_hi:[1,0]
	v_pk_mul_f32 v[50:51], v[54:55], v[50:51]
	v_rcp_f32_e32 v52, v52
	v_rcp_f32_e32 v53, v53
	v_pk_mul_f32 v[54:55], v[64:65], v[58:59] op_sel_hi:[0,1]
	v_pk_mul_f32 v[48:49], v[48:49], v[54:55]
	v_pk_mul_f32 v[40:41], v[44:45], v[40:41]
	v_cvt_pk_bf16_f32 v58, v48, v49
	v_pk_mul_f32 v[48:49], v[64:65], v[52:53] op_sel_hi:[0,1]
	v_pk_mul_f32 v[48:49], v[50:51], v[48:49]
	v_mul_f32_e32 v50, 0xbfb8aa3b, v143
	v_pk_mul_f32 v[52:53], v[44:45], v[50:51] op_sel_hi:[1,0]
	v_pk_mul_f32 v[44:45], v[46:47], v[50:51] op_sel_hi:[1,0]
	v_exp_f32_e32 v52, v52
	v_exp_f32_e32 v53, v53
	v_exp_f32_e32 v44, v44
	v_exp_f32_e32 v45, v45
	v_cvt_pk_bf16_f32 v59, v48, v49
	v_pk_add_f32 v[52:53], v[52:53], 1.0 op_sel_hi:[1,0]
	v_mad_i64_i32 v[48:49], s[14:15], v65, s59, v[112:113]
	v_rcp_f32_e32 v52, v52
	v_rcp_f32_e32 v53, v53
	v_pk_add_f32 v[44:45], v[44:45], 1.0 op_sel_hi:[1,0]
	v_lshl_add_u64 v[48:49], v[48:49], 0, v[114:115]
	v_rcp_f32_e32 v44, v44
	v_rcp_f32_e32 v45, v45
	global_store_dwordx4 v[48:49], v[56:59], off sc1 nt
	v_mul_f32_e32 v48, v143, v143
	v_pk_mul_f32 v[42:43], v[46:47], v[42:43]
; __device__ __forceinline__ unsigned cvt_pk_bf16(float lo, float hi) { unsigned r; asm volatile("v_cvt_pk_bf16_f32 %0, %1, %2" : "=v"(r) : "v"(lo), "v"(hi)); return r; }
;     __device__ __forceinline__ void operator()(const f32x4 (&acc)[2][2][4][2], const Unit& u, int ui, int wr, int wc, int fr, int fq) const {
;     ...
;         for (int ai = 0; ai < 2; ++ai)
; #pragma unroll
;             for (int m = 0; m < 4; ++m) { const float r = rs[ai][m]; const int row = row0 + ai * HALF + m * 16;
;                 const float c1 = r * -1.44269504089f, r2 = r * r; u32x4 w;
; #pragma unroll
;                 for (int n = 0; n < 2; ++n)
; #pragma unroll
;                     for (int p = 0; p < 2; ++p) { const f32x2 g = (f32x2){acc[ai][0][m][n][2 * p], acc[ai][0][m][n][2 * p + 1]}, uu = (f32x2){acc[ai][1][m][n][2 * p], acc[ai][1][m][n][2 * p + 1]};
;                         const f32x2 t = g * c1; f32x2 d; d.x = __builtin_amdgcn_exp2f(t.x); d.y = __builtin_amdgcn_exp2f(t.y); d = d + 1.0f;
;                         f32x2 q; q.x = __builtin_amdgcn_rcpf(d.x); q.y = __builtin_amdgcn_rcpf(d.y);
;                         const f32x2 hh = (g * uu) * (q * r2); w[2 * n + p] = cvt_pk_bf16(hh.x, hh.y); }
;                 __builtin_nontemporal_store(w, (u32x4*)(H + (size_t)row * ldh + col0)); }
	v_pk_mul_f32 v[46:47], v[48:49], v[52:53] op_sel_hi:[0,1]
	v_pk_mul_f32 v[40:41], v[40:41], v[46:47]
	v_pk_mul_f32 v[46:47], v[36:37], v[50:51] op_sel_hi:[1,0]
	v_pk_mul_f32 v[44:45], v[48:49], v[44:45] op_sel_hi:[0,1]
	v_exp_f32_e32 v46, v46
	v_exp_f32_e32 v47, v47
	v_pk_mul_f32 v[42:43], v[42:43], v[44:45]
	v_pk_mul_f32 v[44:45], v[38:39], v[50:51] op_sel_hi:[1,0]
	v_cvt_pk_bf16_f32 v40, v40, v41
	v_cvt_pk_bf16_f32 v41, v42, v43
	v_pk_add_f32 v[42:43], v[46:47], 1.0 op_sel_hi:[1,0]
	v_exp_f32_e32 v44, v44
	v_exp_f32_e32 v45, v45
	v_rcp_f32_e32 v42, v42
	v_rcp_f32_e32 v43, v43
	v_pk_mul_f32 v[32:33], v[36:37], v[32:33]
	v_pk_add_f32 v[36:37], v[44:45], 1.0 op_sel_hi:[1,0]
	v_pk_mul_f32 v[34:35], v[38:39], v[34:35]
	v_rcp_f32_e32 v36, v36
	v_rcp_f32_e32 v37, v37
	v_pk_mul_f32 v[38:39], v[48:49], v[42:43] op_sel_hi:[0,1]
	v_pk_mul_f32 v[32:33], v[32:33], v[38:39]
	v_pk_mul_f32 v[24:25], v[28:29], v[24:25]
	v_cvt_pk_bf16_f32 v42, v32, v33
	v_pk_mul_f32 v[32:33], v[48:49], v[36:37] op_sel_hi:[0,1]
	v_pk_mul_f32 v[32:33], v[34:35], v[32:33]
	v_mul_f32_e32 v34, 0xbfb8aa3b, v140
	v_pk_mul_f32 v[36:37], v[28:29], v[34:35] op_sel_hi:[1,0]
	v_pk_mul_f32 v[28:29], v[30:31], v[34:35] op_sel_hi:[1,0]
	v_exp_f32_e32 v36, v36
	v_exp_f32_e32 v37, v37
	v_exp_f32_e32 v28, v28
	v_exp_f32_e32 v29, v29
	v_cvt_pk_bf16_f32 v43, v32, v33
	v_pk_add_f32 v[36:37], v[36:37], 1.0 op_sel_hi:[1,0]
	v_add_u32_e32 v32, 0x90, v167
	v_rcp_f32_e32 v36, v36
	v_rcp_f32_e32 v37, v37
	v_mad_i64_i32 v[32:33], s[14:15], v32, s59, v[112:113]
	v_pk_add_f32 v[28:29], v[28:29], 1.0 op_sel_hi:[1,0]
	v_lshl_add_u64 v[32:33], v[32:33], 0, v[114:115]
	v_rcp_f32_e32 v28, v28
	v_rcp_f32_e32 v29, v29
	global_store_dwordx4 v[32:33], v[40:43], off nt
	v_mul_f32_e32 v32, v140, v140
	v_pk_mul_f32 v[26:27], v[30:31], v[26:27]
	v_pk_mul_f32 v[30:31], v[32:33], v[36:37] op_sel_hi:[0,1]
	v_pk_mul_f32 v[24:25], v[24:25], v[30:31]
	v_pk_mul_f32 v[30:31], v[20:21], v[34:35] op_sel_hi:[1,0]
	v_pk_mul_f32 v[28:29], v[32:33], v[28:29] op_sel_hi:[0,1]
	v_exp_f32_e32 v30, v30
	v_exp_f32_e32 v31, v31
	v_pk_mul_f32 v[26:27], v[26:27], v[28:29]
	v_pk_mul_f32 v[28:29], v[22:23], v[34:35] op_sel_hi:[1,0]
	v_cvt_pk_bf16_f32 v24, v24, v25
	v_cvt_pk_bf16_f32 v25, v26, v27
	v_pk_add_f32 v[26:27], v[30:31], 1.0 op_sel_hi:[1,0]
	v_exp_f32_e32 v28, v28
	v_exp_f32_e32 v29, v29
	v_rcp_f32_e32 v26, v26
	v_rcp_f32_e32 v27, v27
	v_pk_mul_f32 v[16:17], v[20:21], v[16:17]
	v_pk_add_f32 v[20:21], v[28:29], 1.0 op_sel_hi:[1,0]
	v_pk_mul_f32 v[18:19], v[22:23], v[18:19]
	v_rcp_f32_e32 v20, v20
	v_rcp_f32_e32 v21, v21
	v_pk_mul_f32 v[22:23], v[32:33], v[26:27] op_sel_hi:[0,1]
	v_pk_mul_f32 v[16:17], v[16:17], v[22:23]
	v_pk_mul_f32 v[8:9], v[12:13], v[8:9]
	v_cvt_pk_bf16_f32 v26, v16, v17
	v_pk_mul_f32 v[16:17], v[32:33], v[20:21] op_sel_hi:[0,1]
	v_pk_mul_f32 v[16:17], v[18:19], v[16:17]
	v_mul_f32_e32 v18, 0xbfb8aa3b, v141
	v_pk_mul_f32 v[20:21], v[12:13], v[18:19] op_sel_hi:[1,0]
	v_pk_mul_f32 v[12:13], v[14:15], v[18:19] op_sel_hi:[1,0]
	v_exp_f32_e32 v20, v20
	v_exp_f32_e32 v21, v21
	v_exp_f32_e32 v12, v12
	v_exp_f32_e32 v13, v13
	v_cvt_pk_bf16_f32 v27, v16, v17
	v_pk_add_f32 v[20:21], v[20:21], 1.0 op_sel_hi:[1,0]
	v_add_u32_e32 v16, 0xa0, v167
	v_rcp_f32_e32 v20, v20
	v_rcp_f32_e32 v21, v21
	v_mad_i64_i32 v[16:17], s[14:15], v16, s59, v[112:113]
	v_pk_add_f32 v[12:13], v[12:13], 1.0 op_sel_hi:[1,0]
	v_lshl_add_u64 v[16:17], v[16:17], 0, v[114:115]
	v_rcp_f32_e32 v12, v12
	v_rcp_f32_e32 v13, v13
	global_store_dwordx4 v[16:17], v[24:27], off sc1 nt
	v_mul_f32_e32 v16, v141, v141
	v_pk_mul_f32 v[10:11], v[14:15], v[10:11]
	v_pk_mul_f32 v[14:15], v[16:17], v[20:21] op_sel_hi:[0,1]
	v_pk_mul_f32 v[8:9], v[8:9], v[14:15]
	v_pk_mul_f32 v[14:15], v[4:5], v[18:19] op_sel_hi:[1,0]
	v_pk_mul_f32 v[12:13], v[16:17], v[12:13] op_sel_hi:[0,1]
	v_exp_f32_e32 v14, v14
	v_exp_f32_e32 v15, v15
	v_pk_mul_f32 v[10:11], v[10:11], v[12:13]
	v_pk_mul_f32 v[12:13], v[6:7], v[18:19] op_sel_hi:[1,0]
	v_cvt_pk_bf16_f32 v8, v8, v9
	v_cvt_pk_bf16_f32 v9, v10, v11
	v_pk_add_f32 v[10:11], v[14:15], 1.0 op_sel_hi:[1,0]
	v_exp_f32_e32 v12, v12
	v_exp_f32_e32 v13, v13
	v_rcp_f32_e32 v10, v10
	v_rcp_f32_e32 v11, v11
	v_pk_mul_f32 v[0:1], v[4:5], v[0:1]
	v_pk_add_f32 v[4:5], v[12:13], 1.0 op_sel_hi:[1,0]
	v_pk_mul_f32 v[2:3], v[6:7], v[2:3]
	v_rcp_f32_e32 v4, v4
	v_rcp_f32_e32 v5, v5
	v_pk_mul_f32 v[6:7], v[16:17], v[10:11] op_sel_hi:[0,1]
	v_pk_mul_f32 v[0:1], v[0:1], v[6:7]
	s_andn2_b64 vcc, exec, s[8:9]
	v_cvt_pk_bf16_f32 v10, v0, v1
	v_pk_mul_f32 v[0:1], v[16:17], v[4:5] op_sel_hi:[0,1]
	v_pk_mul_f32 v[0:1], v[2:3], v[0:1]
	s_mov_b64 s[8:9], -1
	v_cvt_pk_bf16_f32 v11, v0, v1
	v_add_u32_e32 v0, 0xb0, v167
	v_mad_i64_i32 v[0:1], s[14:15], v0, s59, v[112:113]
	v_lshl_add_u64 v[0:1], v[0:1], 0, v[114:115]
	global_store_dwordx4 v[0:1], v[8:11], off nt
	s_cbranch_vccnz .LBB0_442
	s_andn2_b64 vcc, exec, s[0:1]
	s_cbranch_vccnz .LBB0_441
	s_barrier
	s_branch .LBB0_441
